# GEMM phase prologue: K-tile 1 stages issued before the first wait (strategy 2 on the four GEMM prologues), on top of hybrid 2
# baseline (speedup 1.0000x reference)
; #define PG8_STAGE(bufoff, gbase, voff) do { _Pragma("unroll") for (int _i = 0; _i < 2; ++_i) \
;         __builtin_amdgcn_global_load_lds((const unsigned*)((const char*)(gbase) + (voff)[_i]), (PG8_LAS unsigned*)(lds + (bufoff) + ldsw + _i * 8192), 16, 0, 0); } while (0)
; #define PG8_WAIT_V(n) asm volatile("s_waitcnt vmcnt(" #n ")" ::: "memory")
; #define PG8_BAR __builtin_amdgcn_s_barrier()
; template <class Epi, class Sched, bool ALIGN_EPI = false, bool SP2 = false>
; __device__ __forceinline__ void gemm_phase(PG8_LAS unsigned char* lds, const Gemm g, const Sched& S, const Epi& E) {
;     ...
;     for (int i = 0; i < 2; ++i) { int R, C; stage_rc(tid * 16 + i * 8192, R, C); const int Rb = Epi::PERM ? ((R & ~31) + perm32(R & 31)) : R;
;         voffA[i] = (unsigned)(R * K + C) * 2u; voffB[i] = (unsigned)(Rb * K + C) * 2u; }
;     const size_t kstep = (size_t)(BK * 2);
;     const size_t hstep = (size_t)HALF * K * 2;
;     const size_t tstep = 2 * hstep;
;     const unsigned ldsw = (unsigned)wid * 1024u;
;     const int aoff = lds_byte(wr * 64 + fr, fq * 8), boff = lds_byte(wc * 32 + fr, fq * 8);
;     ...
;         PG8_STAGE(PG8_SB(0, 0), cB, voffB); PG8_STAGE(PG8_SB(0, 1), cB + hstep, voffB); PG8_STAGE(PG8_SA(0, 0), cA, voffA); PG8_STAGE(PG8_SA(0, 1), cA + hstep, voffA);
;         if (wr == 1) PG8_BAR;
;         PG8_WAIT_V(2); PG8_BAR;
;         PG8_STAGE(PG8_SB(1, 0), cB + kstep, voffB); PG8_STAGE(PG8_SA(1, 0), cA + kstep, voffA); PG8_STAGE(PG8_SB(1, 1), cB + hstep + kstep, voffB);
;         PG8_WAIT_V(6); PG8_BAR;
.LBB0_132:
	s_waitcnt lgkmcnt(0)
	s_add_u32 s36, s40, 0x1ce00000
	s_addc_u32 s37, s41, 0
	s_add_u32 s40, s38, 0x1c0000
	s_addc_u32 s41, s39, 0
	s_lshl_b32 s38, s42, 5
	s_and_b32 s44, s38, 0x60
	s_add_i32 m0, s75, 0x18000
	v_lshl_add_u64 v[8:9], v[8:9], 0, s[30:31]
	s_lshl_b32 s43, s23, 13
	s_lshl_b32 s42, s44, 7
	global_load_lds_dwordx4 v[8:9], off
	v_lshl_add_u64 v[6:7], v[6:7], 0, s[30:31]
	s_add_i32 m0, s75, 0x1a000
	s_add_i32 s79, s75, 0x8000
	s_add_i32 s80, s75, 0xa000
	global_load_lds_dwordx4 v[6:7], off
	v_lshl_add_u64 v[2:3], v[2:3], 0, s[30:31]
	s_mov_b32 m0, s79
	s_add_u32 s38, s34, 0x80080
	global_load_lds_dwordx4 v[2:3], off
	v_lshl_add_u64 v[2:3], v[4:5], 0, s[30:31]
	s_mov_b32 m0, s80
	s_addc_u32 s39, s35, 0
	global_load_lds_dwordx4 v[2:3], off
	s_add_i32 m0, s75, 0x1c000
	v_lshl_add_u64 v[2:3], s[38:39], 0, v[0:1]
	global_load_lds_dwordx4 v[2:3], off
	v_lshl_add_u64 v[2:3], s[38:39], 0, v[130:131]
	s_add_i32 m0, s75, 0x1e000
	s_cmpk_lt_u32 s22, 0x100
	global_load_lds_dwordx4 v[2:3], off
	s_waitcnt vmcnt(8)
	s_barrier
	v_lshrrev_b32_e32 v3, 1, v10
	v_and_b32_e32 v3, 24, v3
	v_and_b32_e32 v2, 15, v10
	v_lshlrev_b32_e32 v4, 1, v3
	v_lshl_or_b32 v148, s23, 6, v2
	v_lshl_or_b32 v2, v2, 6, v4
	v_lshlrev_b32_e32 v4, 2, v10
	v_and_b32_e32 v4, 32, v4
	v_bitop3_b32 v5, v2, s43, v4 bitop3:0xde
	v_bitop3_b32 v149, v2, s42, v4 bitop3:0xde
	v_lshlrev_b32_e32 v2, 15, v15
	v_and_b32_e32 v2, 0xffff0000, v2
	v_or_b32_e32 v150, s44, v3
	v_lshl_add_u32 v2, v14, 12, v2
	v_and_b32_e32 v3, 1, v15
	v_lshl_or_b32 v2, v3, 6, v2
	v_lshl_add_u32 v136, v16, 1, v2
	v_lshlrev_b32_e32 v2, 15, v11
	v_and_b32_e32 v2, 0xffff0000, v2
	s_waitcnt vmcnt(6)
	v_lshl_add_u32 v2, v12, 12, v2
	v_and_b32_e32 v3, 1, v11
	v_lshl_or_b32 v2, v3, 6, v2
	v_readlane_b32 s22, v255, 31
	s_cselect_b64 s[42:43], -1, 0
	v_mov_b32_e32 v137, v1
	v_lshl_add_u32 v138, v13, 1, v2
	v_mov_b32_e32 v139, v1
	s_mov_b32 s81, 0
	v_add_u32_e32 v151, 0, v5
	v_readlane_b32 s82, v255, 15
	s_mov_b32 s83, s22
	s_barrier
	v_readlane_b32 s23, v255, 32
	s_branch .LBB0_135

; #define PG8_STAGE(bufoff, gbase, voff) do { _Pragma("unroll") for (int _i = 0; _i < 2; ++_i) \
;         __builtin_amdgcn_global_load_lds((const unsigned*)((const char*)(gbase) + (voff)[_i]), (PG8_LAS unsigned*)(lds + (bufoff) + ldsw + _i * 8192), 16, 0, 0); } while (0)
; #define PG8_WAIT_V(n) asm volatile("s_waitcnt vmcnt(" #n ")" ::: "memory")
; #define PG8_BAR __builtin_amdgcn_s_barrier()
; template <class Epi, class Sched, bool ALIGN_EPI = false, bool SP2 = false>
; __device__ __forceinline__ void gemm_phase(PG8_LAS unsigned char* lds, const Gemm g, const Sched& S, const Epi& E) {
;     ...
;     for (int i = 0; i < 2; ++i) { int R, C; stage_rc(tid * 16 + i * 8192, R, C); const int Rb = Epi::PERM ? ((R & ~31) + perm32(R & 31)) : R;
;         voffA[i] = (unsigned)(R * K + C) * 2u; voffB[i] = (unsigned)(Rb * K + C) * 2u; }
;     const size_t kstep = (size_t)(BK * 2);
;     const size_t hstep = (size_t)HALF * K * 2;
;     const size_t tstep = 2 * hstep;
;     const unsigned ldsw = (unsigned)wid * 1024u;
;     const int aoff = lds_byte(wr * 64 + fr, fq * 8), boff = lds_byte(wc * 32 + fr, fq * 8);
;     ...
;         PG8_STAGE(PG8_SB(0, 0), cB, voffB); PG8_STAGE(PG8_SB(0, 1), cB + hstep, voffB); PG8_STAGE(PG8_SA(0, 0), cA, voffA); PG8_STAGE(PG8_SA(0, 1), cA + hstep, voffA);
;         if (wr == 1) PG8_BAR;
;         PG8_WAIT_V(2); PG8_BAR;
;         PG8_STAGE(PG8_SB(1, 0), cB + kstep, voffB); PG8_STAGE(PG8_SA(1, 0), cA + kstep, voffA); PG8_STAGE(PG8_SB(1, 1), cB + hstep + kstep, voffB);
;         PG8_WAIT_V(6); PG8_BAR;
.LBB0_561:
	v_lshrrev_b32_e32 v18, 1, v13
	s_waitcnt lgkmcnt(0)
	s_add_u32 s36, s36, 0x2d600000
	v_and_b32_e32 v18, 24, v18
	s_addc_u32 s37, s37, 0
	v_and_b32_e32 v17, 15, v13
	v_lshlrev_b32_e32 v19, 1, v18
	v_lshlrev_b32_e32 v13, 2, v13
	s_lshl_b32 s23, s23, 5
	v_lshl_or_b32 v140, s40, 6, v17
	v_lshl_or_b32 v17, v17, 6, v19
	s_lshl_b32 s40, s40, 13
	v_and_b32_e32 v13, 32, v13
	s_and_b32 s23, s23, 0x60
	s_add_i32 m0, s75, 0x18000
	v_lshl_add_u64 v[8:9], v[8:9], 0, s[30:31]
	v_bitop3_b32 v19, v17, s40, v13 bitop3:0xde
	s_lshl_b32 s40, s23, 7
	global_load_lds_dwordx4 v[8:9], off
	v_lshl_add_u64 v[6:7], v[6:7], 0, s[30:31]
	s_add_i32 m0, s75, 0x1a000
	s_add_i32 s79, s75, 0x8000
	s_add_i32 s80, s75, 0xa000
	v_bitop3_b32 v141, v17, s40, v13 bitop3:0xde
	global_load_lds_dwordx4 v[6:7], off
	v_lshl_add_u64 v[2:3], v[2:3], 0, s[30:31]
	s_mov_b32 m0, s79
	s_add_u32 s40, s34, 0x80080
	global_load_lds_dwordx4 v[2:3], off
	v_lshl_add_u64 v[2:3], v[4:5], 0, s[30:31]
	s_mov_b32 m0, s80
	s_addc_u32 s41, s35, 0
	global_load_lds_dwordx4 v[2:3], off
	s_add_i32 m0, s75, 0x1c000
	v_lshl_add_u64 v[2:3], s[40:41], 0, v[0:1]
	global_load_lds_dwordx4 v[2:3], off
	v_lshl_add_u64 v[2:3], s[40:41], 0, v[130:131]
	s_add_i32 m0, s75, 0x1e000
	s_cmpk_lt_u32 s22, 0x100
	global_load_lds_dwordx4 v[2:3], off
	s_waitcnt vmcnt(8)
	s_barrier
	v_lshlrev_b32_e32 v2, 15, v15
	v_and_b32_e32 v2, 0xffff0000, v2
	v_lshl_add_u32 v2, v14, 12, v2
	v_and_b32_e32 v3, 1, v15
	v_lshl_or_b32 v2, v3, 6, v2
	v_lshl_add_u32 v136, v16, 1, v2
	v_lshlrev_b32_e32 v2, 15, v10
	v_and_b32_e32 v2, 0xffff0000, v2
	s_waitcnt vmcnt(6)
	v_lshl_add_u32 v2, v11, 12, v2
	v_and_b32_e32 v3, 1, v10
	v_or_b32_e32 v142, s23, v18
	v_lshl_or_b32 v2, v3, 6, v2
	v_readlane_b32 s22, v255, 35
	s_cselect_b64 s[42:43], -1, 0
	v_mov_b32_e32 v137, v1
	v_lshl_add_u32 v138, v12, 1, v2
	v_mov_b32_e32 v139, v1
	s_mov_b32 s81, 0
	v_add_u32_e32 v143, 0, v19
	v_readlane_b32 s82, v255, 18
	s_mov_b32 s83, s22
	s_barrier
	v_readlane_b32 s23, v255, 36
	s_branch .LBB0_564

; #define PG8_STAGE(bufoff, gbase, voff) do { _Pragma("unroll") for (int _i = 0; _i < 2; ++_i) \
;         __builtin_amdgcn_global_load_lds((const unsigned*)((const char*)(gbase) + (voff)[_i]), (PG8_LAS unsigned*)(lds + (bufoff) + ldsw + _i * 8192), 16, 0, 0); } while (0)
; #define PG8_WAIT_V(n) asm volatile("s_waitcnt vmcnt(" #n ")" ::: "memory")
; #define PG8_BAR __builtin_amdgcn_s_barrier()
; template <class Epi, class Sched, bool ALIGN_EPI = false, bool SP2 = false>
; __device__ __forceinline__ void gemm_phase(PG8_LAS unsigned char* lds, const Gemm g, const Sched& S, const Epi& E) {
;     ...
;     for (int i = 0; i < 2; ++i) { int R, C; stage_rc(tid * 16 + i * 8192, R, C); const int Rb = Epi::PERM ? ((R & ~31) + perm32(R & 31)) : R;
;         voffA[i] = (unsigned)(R * K + C) * 2u; voffB[i] = (unsigned)(Rb * K + C) * 2u; }
;     const size_t kstep = (size_t)(BK * 2);
;     const size_t hstep = (size_t)HALF * K * 2;
;     const size_t tstep = 2 * hstep;
;     const unsigned ldsw = (unsigned)wid * 1024u;
;     const int aoff = lds_byte(wr * 64 + fr, fq * 8), boff = lds_byte(wc * 32 + fr, fq * 8);
;     ...
;         PG8_STAGE(PG8_SB(0, 0), cB, voffB); PG8_STAGE(PG8_SB(0, 1), cB + hstep, voffB); PG8_STAGE(PG8_SA(0, 0), cA, voffA); PG8_STAGE(PG8_SA(0, 1), cA + hstep, voffA);
;         if (wr == 1) PG8_BAR;
;         PG8_WAIT_V(2); PG8_BAR;
;         PG8_STAGE(PG8_SB(1, 0), cB + kstep, voffB); PG8_STAGE(PG8_SA(1, 0), cA + kstep, voffA); PG8_STAGE(PG8_SB(1, 1), cB + hstep + kstep, voffB);
;         PG8_WAIT_V(6); PG8_BAR;
.LBB0_698:
	s_waitcnt lgkmcnt(0)
	s_add_u32 s36, s42, 0x1ce00000
	s_addc_u32 s37, s43, 0
	v_lshrrev_b32_e32 v18, 1, v12
	s_add_u32 s42, s40, 0x1c0000
	v_and_b32_e32 v18, 24, v18
	s_addc_u32 s43, s41, 0
	v_and_b32_e32 v17, 15, v12
	v_lshlrev_b32_e32 v19, 1, v18
	v_lshlrev_b32_e32 v12, 2, v12
	s_lshl_b32 s23, s23, 5
	v_lshl_or_b32 v148, s44, 6, v17
	v_lshl_or_b32 v17, v17, 6, v19
	s_lshl_b32 s40, s44, 13
	v_and_b32_e32 v12, 32, v12
	s_and_b32 s23, s23, 0x60
	s_add_i32 m0, s75, 0x18000
	v_lshl_add_u64 v[8:9], v[8:9], 0, s[30:31]
	v_bitop3_b32 v19, v17, s40, v12 bitop3:0xde
	s_lshl_b32 s40, s23, 7
	global_load_lds_dwordx4 v[8:9], off
	v_lshl_add_u64 v[6:7], v[6:7], 0, s[30:31]
	s_add_i32 m0, s75, 0x1a000
	s_add_i32 s79, s75, 0x8000
	s_add_i32 s80, s75, 0xa000
	v_bitop3_b32 v149, v17, s40, v12 bitop3:0xde
	global_load_lds_dwordx4 v[6:7], off
	v_lshl_add_u64 v[2:3], v[2:3], 0, s[30:31]
	s_mov_b32 m0, s79
	s_add_u32 s40, s34, 0x80080
	global_load_lds_dwordx4 v[2:3], off
	v_lshl_add_u64 v[2:3], v[4:5], 0, s[30:31]
	s_mov_b32 m0, s80
	s_addc_u32 s41, s35, 0
	global_load_lds_dwordx4 v[2:3], off
	s_add_i32 m0, s75, 0x1c000
	v_lshl_add_u64 v[2:3], s[40:41], 0, v[0:1]
	global_load_lds_dwordx4 v[2:3], off
	v_lshl_add_u64 v[2:3], s[40:41], 0, v[130:131]
	s_add_i32 m0, s75, 0x1e000
	s_cmpk_lt_u32 s22, 0x100
	global_load_lds_dwordx4 v[2:3], off
	s_waitcnt vmcnt(8)
	s_barrier
	v_lshlrev_b32_e32 v2, 15, v15
	v_and_b32_e32 v2, 0xffff0000, v2
	v_lshl_add_u32 v2, v14, 12, v2
	v_and_b32_e32 v3, 1, v15
	v_lshl_or_b32 v2, v3, 6, v2
	v_lshl_add_u32 v136, v16, 1, v2
	v_lshlrev_b32_e32 v2, 15, v10
	v_and_b32_e32 v2, 0xffff0000, v2
	s_waitcnt vmcnt(6)
	v_lshl_add_u32 v2, v11, 12, v2
	v_and_b32_e32 v3, 1, v10
	v_or_b32_e32 v150, s23, v18
	v_lshl_or_b32 v2, v3, 6, v2
	v_readlane_b32 s22, v255, 39
	s_cselect_b64 s[44:45], -1, 0
	v_mov_b32_e32 v137, v1
	v_lshl_add_u32 v138, v13, 1, v2
	v_mov_b32_e32 v139, v1
	s_mov_b32 s81, 0
	v_add_u32_e32 v151, 0, v19
	v_readlane_b32 s82, v255, 21
	s_mov_b32 s83, s22
	s_barrier
	v_readlane_b32 s23, v255, 40
	s_branch .LBB0_701

; #define PG8_STAGE(bufoff, gbase, voff) do { _Pragma("unroll") for (int _i = 0; _i < 2; ++_i) \
;         __builtin_amdgcn_global_load_lds((const unsigned*)((const char*)(gbase) + (voff)[_i]), (PG8_LAS unsigned*)(lds + (bufoff) + ldsw + _i * 8192), 16, 0, 0); } while (0)
; #define PG8_WAIT_V(n) asm volatile("s_waitcnt vmcnt(" #n ")" ::: "memory")
; #define PG8_BAR __builtin_amdgcn_s_barrier()
; template <class Epi, class Sched, bool ALIGN_EPI = false, bool SP2 = false>
; __device__ __forceinline__ void gemm_phase(PG8_LAS unsigned char* lds, const Gemm g, const Sched& S, const Epi& E) {
;     ...
;     for (int i = 0; i < 2; ++i) { int R, C; stage_rc(tid * 16 + i * 8192, R, C); const int Rb = Epi::PERM ? ((R & ~31) + perm32(R & 31)) : R;
;         voffA[i] = (unsigned)(R * K + C) * 2u; voffB[i] = (unsigned)(Rb * K + C) * 2u; }
;     const size_t kstep = (size_t)(BK * 2);
;     const size_t hstep = (size_t)HALF * K * 2;
;     const size_t tstep = 2 * hstep;
;     const unsigned ldsw = (unsigned)wid * 1024u;
;     const int aoff = lds_byte(wr * 64 + fr, fq * 8), boff = lds_byte(wc * 32 + fr, fq * 8);
;     ...
;         PG8_STAGE(PG8_SB(0, 0), cB, voffB); PG8_STAGE(PG8_SB(0, 1), cB + hstep, voffB); PG8_STAGE(PG8_SA(0, 0), cA, voffA); PG8_STAGE(PG8_SA(0, 1), cA + hstep, voffA);
;         if (wr == 1) PG8_BAR;
;         PG8_WAIT_V(2); PG8_BAR;
;         PG8_STAGE(PG8_SB(1, 0), cB + kstep, voffB); PG8_STAGE(PG8_SA(1, 0), cA + kstep, voffA); PG8_STAGE(PG8_SB(1, 1), cB + hstep + kstep, voffB);
;         PG8_WAIT_V(6); PG8_BAR;
.LBB0_769:
	v_lshrrev_b32_e32 v20, 1, v14
	s_waitcnt lgkmcnt(0)
	s_add_u32 s36, s36, 0x2d600000
	v_and_b32_e32 v20, 24, v20
	s_addc_u32 s37, s37, 0
	v_and_b32_e32 v19, 15, v14
	v_lshlrev_b32_e32 v21, 1, v20
	v_lshlrev_b32_e32 v14, 2, v14
	s_lshl_b32 s23, s23, 5
	v_lshl_or_b32 v140, s38, 6, v19
	v_lshl_or_b32 v19, v19, 6, v21
	s_lshl_b32 s38, s38, 13
	v_and_b32_e32 v14, 32, v14
	s_and_b32 s23, s23, 0x60
	s_add_i32 m0, s57, 0x18000
	v_lshl_add_u64 v[8:9], v[8:9], 0, s[30:31]
	v_bitop3_b32 v21, v19, s38, v14 bitop3:0xde
	s_lshl_b32 s38, s23, 7
	global_load_lds_dwordx4 v[8:9], off
	v_lshl_add_u64 v[6:7], v[6:7], 0, s[30:31]
	s_add_i32 m0, s57, 0x1a000
	s_add_i32 s75, s57, 0x8000
	s_add_i32 s76, s57, 0xa000
	v_bitop3_b32 v141, v19, s38, v14 bitop3:0xde
	global_load_lds_dwordx4 v[6:7], off
	v_lshl_add_u64 v[2:3], v[2:3], 0, s[30:31]
	s_mov_b32 m0, s75
	s_add_u32 s38, s34, 0x160080
	global_load_lds_dwordx4 v[2:3], off
	v_lshl_add_u64 v[2:3], v[4:5], 0, s[30:31]
	s_mov_b32 m0, s76
	s_addc_u32 s39, s35, 0
	global_load_lds_dwordx4 v[2:3], off
	s_add_i32 m0, s57, 0x1c000
	v_lshl_add_u64 v[2:3], s[38:39], 0, v[0:1]
	global_load_lds_dwordx4 v[2:3], off
	v_lshl_add_u64 v[2:3], s[38:39], 0, v[130:131]
	s_add_i32 m0, s57, 0x1e000
	s_movk_i32 s39, 0x1600
	global_load_lds_dwordx4 v[2:3], off
	s_waitcnt vmcnt(8)
	s_barrier
	v_lshrrev_b32_e32 v3, 1, v16
	v_mul_lo_u32 v2, v15, s39
	s_mov_b32 s38, 0x16000
	s_cmpk_lt_u32 s22, 0x100
	v_or_b32_e32 v142, s23, v20
	v_mad_u64_u32 v[2:3], s[22:23], v3, s38, v[2:3]
	v_or_b32_e32 v2, v2, v17
	v_add_lshl_u32 v2, v2, v18, 1
	v_mov_b32_e32 v3, v1
	s_mov_b64 s[40:41], 0x160080
	v_lshl_add_u64 v[136:137], v[2:3], 0, s[40:41]
	v_lshrrev_b32_e32 v3, 1, v10
	v_mul_lo_u32 v2, v11, s39
	v_mad_u64_u32 v[2:3], s[22:23], v3, s38, v[2:3]
	s_waitcnt vmcnt(6)
	v_or_b32_e32 v2, v2, v12
	v_add_lshl_u32 v2, v2, v13, 1
	v_mov_b32_e32 v3, v1
	v_readlane_b32 s22, v255, 35
	s_cselect_b64 s[42:43], -1, 0
	v_lshl_add_u64 v[138:139], v[2:3], 0, s[40:41]
	s_mov_b32 s77, 0
	v_add_u32_e32 v143, 0, v21
	v_readlane_b32 s80, v255, 18
	s_mov_b32 s81, s22
	s_barrier
	v_readlane_b32 s23, v255, 36
	s_branch .LBB0_772
